# P0: counted waits in x->bf16 loop, p->bf16 with 9 loads in flight, rotated transpose-item mapping; P1 PP tile rebalance
# speedup vs baseline: 1.0536x; 1.0137x over previous
.LBB0_5:
	s_or_b64 exec, exec, s[2:3]
	s_load_dwordx16 s[60:75], s[0:1], 0xc0
	v_mov_b32_e32 v128, v0
	s_movk_i32 s2, 0x1180
	v_ashrrev_i32_e32 v129, 6, v128
	s_add_u32 s97, s59, 0x80
	s_and_b32 s97, s97, 0xff
	s_cmpk_lg_i32 s58, 0x100
	s_cselect_b32 s97, s59, s97
	v_lshl_add_u32 v1, s97, 3, v129
	v_and_b32_e32 v130, 63, v128
	v_cmp_gt_i32_e32 vcc, s2, v1
	v_lshlrev_b32_e32 v83, 2, v128
	s_and_saveexec_b64 s[2:3], vcc
	s_cbranch_execz .LBB0_38
	s_movk_i32 s4, 0x2100
	v_mul_lo_u32 v2, v129, s4
	v_lshrrev_b32_e32 v56, 5, v130
	v_add_u32_e32 v8, 0, v2
	v_mul_u32_u24_e32 v2, 0x84, v56
	v_and_b32_e32 v22, 0x7c, v83
	v_add3_u32 v57, v8, v2, v22
	v_lshlrev_b32_e32 v2, 3, v130
	v_and_b32_e32 v2, 56, v2
	s_load_dwordx16 s[36:51], s[0:1], 0x40
	v_lshrrev_b32_e32 v58, 3, v130
	v_mul_u32_u24_e32 v9, 0x84, v2
	v_lshlrev_b32_e32 v2, 1, v2
	v_mov_b32_e32 v3, 0
	v_lshl_add_u64 v[4:5], s[76:77], 0, v[2:3]
	s_mov_b64 s[4:5], 0x1100000
	v_lshlrev_b32_e32 v2, 2, v58
	v_lshl_add_u64 v[6:7], v[4:5], 0, s[4:5]
	v_add3_u32 v59, v8, v9, v2
	s_mov_b64 s[4:5], 0xf00000
	s_lshl_b32 s18, s58, 3
	v_lshlrev_b32_e32 v2, 3, v129
	v_lshl_add_u64 v[8:9], v[4:5], 0, s[4:5]
	s_mov_b64 s[4:5], 0xd00000
	s_waitcnt lgkmcnt(0)
	s_cmp_lg_u64 s[66:67], 0
	v_lshl_add_u32 v63, s97, 6, v2
	v_lshlrev_b32_e32 v2, 1, v129
	v_lshl_add_u64 v[10:11], v[4:5], 0, s[4:5]
	s_mov_b64 s[4:5], 0x900000
	v_mov_b32_e32 v23, v3
	s_cselect_b64 s[6:7], -1, 0
	s_cmp_lg_u64 s[38:39], 0
	v_lshl_add_u32 v64, s97, 4, v2
	v_lshlrev_b32_e32 v2, 6, v129
	v_or_b32_e32 v60, 8, v58
	v_or_b32_e32 v61, 16, v58
	v_or_b32_e32 v62, 24, v58
	v_lshl_add_u64 v[12:13], v[4:5], 0, s[4:5]
	v_lshl_add_u64 v[14:15], s[70:71], 0, v[22:23]
	v_lshl_add_u64 v[16:17], s[68:69], 0, v[22:23]
	v_lshl_add_u64 v[18:19], s[60:61], 0, v[22:23]
	v_lshl_add_u64 v[20:21], s[64:65], 0, v[22:23]
	v_lshl_add_u64 v[22:23], s[36:37], 0, v[22:23]
	s_mov_b64 s[4:5], 0
	s_cselect_b64 s[8:9], -1, 0
	s_lshl_b32 s19, s58, 6
	s_lshl_b32 s20, s58, 4
	v_lshl_add_u32 v65, s97, 9, v2
	s_lshl_b32 s21, s58, 9
	s_movk_i32 s22, 0x8ff
	s_movk_i32 s23, 0xcff
	s_movk_i32 s24, 0xeff
	s_movk_i32 s25, 0x10ff
	s_mov_b32 s26, 0x12000
	s_movk_i32 s27, 0x3ff
	s_movk_i32 s28, 0x7ff
	s_movk_i32 s29, 0xdff
	s_movk_i32 s30, 0x117f
	v_add_u32_e32 v66, 0x400, v57
	v_add_u32_e32 v67, 0x800, v57
	v_add_u32_e32 v68, 0xc00, v57
	v_add_u32_e32 v69, 0x1000, v57
	v_add_u32_e32 v70, 0x1400, v57
	v_add_u32_e32 v71, 0x1800, v57
	v_add_u32_e32 v72, 0x1c00, v57
	s_branch .LBB0_9

.LBB0_40:
	s_or_b64 exec, exec, s[10:11]
	s_add_i32 s12, s12, s14
	s_and_b64 vcc, exec, s[8:9]
	s_barrier
	s_cbranch_vccnz .LBB0_48
	s_add_i32 s16, s16, s58
	s_cmpk_gt_i32 s16, 0x41f
	s_waitcnt vmcnt(11)
	v_mov_b64_e32 v[76:77], v[8:9]
	s_waitcnt vmcnt(9)
	v_mov_b64_e32 v[68:69], v[28:29]
	s_waitcnt vmcnt(7)
	v_mov_b64_e32 v[60:61], v[36:37]
	s_waitcnt vmcnt(5)
	v_mov_b64_e32 v[52:53], v[44:45]
	v_mov_b64_e32 v[80:81], v[20:21]
	v_mov_b64_e32 v[72:73], v[32:33]
	v_mov_b64_e32 v[64:65], v[40:41]
	s_waitcnt vmcnt(4)
	v_mov_b64_e32 v[56:57], v[48:49]
	s_cselect_b64 s[8:9], -1, 0
	v_mov_b64_e32 v[74:75], v[6:7]
	v_mov_b64_e32 v[66:67], v[26:27]
	v_mov_b64_e32 v[58:59], v[34:35]
	v_mov_b64_e32 v[50:51], v[42:43]
	v_mov_b64_e32 v[78:79], v[18:19]
	v_mov_b64_e32 v[70:71], v[30:31]
	v_mov_b64_e32 v[62:63], v[38:39]
	v_mov_b64_e32 v[54:55], v[46:47]
	s_branch .Lp0b_join

.Lp0b_join:
	s_and_b64 vcc, exec, s[8:9]
	s_cbranch_vccnz .LBB0_43
	v_add_u32_e32 v6, s12, v95
	v_readlane_b32 s36, v242, 21
	v_add_u32_e32 v8, 0xffffc000, v6
	v_cmp_gt_i32_e32 vcc, s13, v6
	v_readlane_b32 s37, v242, 22
	v_readlane_b32 s39, v242, 24
	v_ashrrev_i32_e32 v7, 31, v6
	v_cndmask_b32_e32 v6, v8, v6, vcc
	v_readlane_b32 s38, v242, 23
	v_mov_b32_e32 v8, s39
	v_mov_b32_e32 v9, s37
	v_cndmask_b32_e32 v7, 0, v7, vcc
	v_cndmask_b32_e32 v9, v8, v9, vcc
	v_mov_b32_e32 v8, s38
	v_mov_b32_e32 v18, s36
	v_cndmask_b32_e32 v8, v8, v18, vcc
	v_lshlrev_b64 v[6:7], 12, v[6:7]
	v_lshl_add_u64 v[6:7], v[8:9], 0, v[6:7]
	v_lshl_add_u64 v[6:7], v[88:89], 2, v[6:7]
	v_lshl_add_u64 v[46:47], v[6:7], 0, v[84:85]
	global_load_dwordx4 v[6:9], v[46:47], off offset:16
	global_load_dwordx4 v[18:21], v[46:47], off
	global_load_dwordx4 v[26:29], v[46:47], off offset:144
	global_load_dwordx4 v[30:33], v[46:47], off offset:128
	global_load_dwordx4 v[34:37], v[46:47], off offset:272
	global_load_dwordx4 v[38:41], v[46:47], off offset:256
	global_load_dwordx4 v[42:45], v[46:47], off offset:400
	s_nop 0
	global_load_dwordx4 v[46:49], v[46:47], off offset:384
	v_readlane_b32 s40, v242, 25
	v_readlane_b32 s41, v242, 26
	v_readlane_b32 s42, v242, 27
	v_readlane_b32 s43, v242, 28
	v_readlane_b32 s44, v242, 29
	v_readlane_b32 s45, v242, 30
	v_readlane_b32 s46, v242, 31
	v_readlane_b32 s47, v242, 32
	v_readlane_b32 s48, v242, 33
	v_readlane_b32 s49, v242, 34
	v_readlane_b32 s50, v242, 35
	v_readlane_b32 s51, v242, 36

.LBB0_48:
	s_add_u32 s0, s76, 0x3280000
	s_addc_u32 s1, s77, 0
	s_lshl_b32 s33, s59, 9
	s_waitcnt vmcnt(11)
	v_add_u32_e32 v8, s33, v128
	s_cmpk_lg_i32 s58, 0x100
	s_cbranch_scc1 .Lp0c_orig
	v_readlane_b32 s20, v242, 25
	v_readlane_b32 s21, v242, 26
	v_readlane_b32 s22, v242, 27
	v_readlane_b32 s23, v242, 28
	v_lshlrev_b32_e32 v9, 4, v8
	v_lshlrev_b32_e32 v7, 3, v8
	s_mov_b64 s[6:7], s[0:1]
	s_add_u32 s8, s0, 0x800000
	s_addc_u32 s9, s1, 0
	s_nop 1
	s_cmp_lt_u32 s59, 64
	s_cbranch_scc0 .Lp0c_no8a
	global_load_dwordx4 v[42:45], v9, s[22:23]
.Lp0c_no8a:
	global_load_dwordx4 v[10:13], v9, s[20:21]
	s_add_u32 s20, s20, 0x200000
	s_addc_u32 s21, s21, 0
	global_load_dwordx4 v[14:17], v9, s[20:21]
	s_add_u32 s20, s20, 0x200000
	s_addc_u32 s21, s21, 0
	global_load_dwordx4 v[18:21], v9, s[20:21]
	s_add_u32 s20, s20, 0x200000
	s_addc_u32 s21, s21, 0
	global_load_dwordx4 v[22:25], v9, s[20:21]
	s_add_u32 s20, s20, 0x200000
	s_addc_u32 s21, s21, 0
	global_load_dwordx4 v[26:29], v9, s[20:21]
	s_add_u32 s20, s20, 0x200000
	s_addc_u32 s21, s21, 0
	global_load_dwordx4 v[30:33], v9, s[20:21]
	s_add_u32 s20, s20, 0x200000
	s_addc_u32 s21, s21, 0
	global_load_dwordx4 v[34:37], v9, s[20:21]
	s_add_u32 s20, s20, 0x200000
	s_addc_u32 s21, s21, 0
	global_load_dwordx4 v[38:41], v9, s[20:21]
	s_cmp_lt_u32 s59, 64
	s_cbranch_scc0 .Lp0c_no8b
	s_waitcnt vmcnt(8)
	v_cvt_pk_bf16_f32 v42, v42, v43
	v_cvt_pk_bf16_f32 v43, v44, v45
	global_store_dwordx2 v7, v[42:43], s[8:9]
.Lp0c_no8b:
	s_waitcnt vmcnt(7)
	v_cvt_pk_bf16_f32 v10, v10, v11
	v_cvt_pk_bf16_f32 v11, v12, v13
	global_store_dwordx2 v7, v[10:11], s[6:7]
	s_add_u32 s6, s6, 0x100000
	s_addc_u32 s7, s7, 0
	s_waitcnt vmcnt(7)
	v_cvt_pk_bf16_f32 v14, v14, v15
	v_cvt_pk_bf16_f32 v15, v16, v17
	global_store_dwordx2 v7, v[14:15], s[6:7]
	s_add_u32 s6, s6, 0x100000
	s_addc_u32 s7, s7, 0
	s_waitcnt vmcnt(7)
	v_cvt_pk_bf16_f32 v18, v18, v19
	v_cvt_pk_bf16_f32 v19, v20, v21
	global_store_dwordx2 v7, v[18:19], s[6:7]
	s_add_u32 s6, s6, 0x100000
	s_addc_u32 s7, s7, 0
	s_waitcnt vmcnt(7)
	v_cvt_pk_bf16_f32 v22, v22, v23
	v_cvt_pk_bf16_f32 v23, v24, v25
	global_store_dwordx2 v7, v[22:23], s[6:7]
	s_add_u32 s6, s6, 0x100000
	s_addc_u32 s7, s7, 0
	s_waitcnt vmcnt(7)
	v_cvt_pk_bf16_f32 v26, v26, v27
	v_cvt_pk_bf16_f32 v27, v28, v29
	global_store_dwordx2 v7, v[26:27], s[6:7]
	s_add_u32 s6, s6, 0x100000
	s_addc_u32 s7, s7, 0
	s_waitcnt vmcnt(7)
	v_cvt_pk_bf16_f32 v30, v30, v31
	v_cvt_pk_bf16_f32 v31, v32, v33
	global_store_dwordx2 v7, v[30:31], s[6:7]
	s_add_u32 s6, s6, 0x100000
	s_addc_u32 s7, s7, 0
	s_waitcnt vmcnt(7)
	v_cvt_pk_bf16_f32 v34, v34, v35
	v_cvt_pk_bf16_f32 v35, v36, v37
	global_store_dwordx2 v7, v[34:35], s[6:7]
	s_add_u32 s6, s6, 0x100000
	s_addc_u32 s7, s7, 0
	s_waitcnt vmcnt(7)
	v_cvt_pk_bf16_f32 v38, v38, v39
	v_cvt_pk_bf16_f32 v39, v40, v41
	global_store_dwordx2 v7, v[38:39], s[6:7]
	s_branch .Lp0c_done
.Lp0c_orig:
	s_mov_b32 s4, 0x108000
	v_cmp_gt_i32_e32 vcc, s4, v8
	s_and_saveexec_b64 s[4:5], vcc
	s_cbranch_execz .LBB0_55
	s_lshl_b32 s10, s58, 9
	v_lshl_add_u32 v9, s59, 11, v83
	s_lshl_b32 s11, s58, 11
	s_mov_b64 s[6:7], 0
	s_movk_i32 s12, 0x3fff
	v_mov_b32_e32 v3, 0
	s_mov_b32 s13, 0x107fff
	s_branch .LBB0_51

.Lp0c_done:
	s_barrier
	s_waitcnt vmcnt(0)
	s_barrier
	s_mov_b64 s[4:5], exec
	v_readlane_b32 s6, v242, 19
	v_readlane_b32 s7, v242, 20
	s_and_b64 s[6:7], s[4:5], s[6:7]
	s_mov_b64 exec, s[6:7]
	s_cbranch_execz .LBB0_107
	s_add_i32 s6, 0, 0x20000
	v_mov_b32_e32 v2, s6
	s_waitcnt vmcnt(0) expcnt(0) lgkmcnt(0)
	ds_read_b32 v4, v2
	s_add_i32 s6, 0, 0x20004
	v_mov_b32_e32 v2, s6
	ds_read_b32 v2, v2
	s_waitcnt lgkmcnt(1)
	v_cmp_ne_u32_e32 vcc, 0, v4
	s_cbranch_vccnz .LBB0_71
	v_readlane_b32 s6, v242, 0
	v_readlane_b32 s7, v242, 1
	s_load_dwordx2 s[10:11], s[6:7], 0x4
	s_add_u32 s6, s76, 0xf46aa00
	s_addc_u32 s7, s77, 0
	s_add_u32 s8, s76, 0xf46ac00
	s_addc_u32 s9, s77, 0
	s_waitcnt lgkmcnt(0)
	s_mul_i32 s48, s10, s58
	s_add_u32 s10, s76, 0xf46ad00
	s_mul_i32 s48, s48, s11
	s_addc_u32 s11, s77, 0
	s_add_u32 s12, s76, 0xf46ae00
	s_addc_u32 s13, s77, 0
	s_add_u32 s14, s76, 0xf46af00
	s_addc_u32 s15, s77, 0
	s_add_u32 s16, s76, 0xf46b000
	s_addc_u32 s17, s77, 0
	s_add_u32 s18, s76, 0xf46b100
	s_addc_u32 s19, s77, 0
	s_add_u32 s20, s76, 0xf46b200
	s_addc_u32 s21, s77, 0
	s_add_u32 s22, s76, 0xf46b300
	s_addc_u32 s23, s77, 0
	s_add_u32 s24, s76, 0xf46b400
	s_addc_u32 s25, s77, 0
	s_add_u32 s26, s76, 0xf46b500
	s_addc_u32 s27, s77, 0
	s_add_u32 s28, s76, 0xf46b600
	s_addc_u32 s29, s77, 0
	s_add_u32 s30, s76, 0xf46b700
	s_addc_u32 s31, s77, 0
	s_add_u32 s34, s76, 0xf46b800
	s_addc_u32 s35, s77, 0
	s_add_u32 s36, s76, 0xf46b900
	s_addc_u32 s37, s77, 0
	s_add_u32 s38, s76, 0xf46ba00
	s_addc_u32 s39, s77, 0
	s_add_u32 s40, s76, 0xf46bb00
	s_addc_u32 s41, s77, 0
	s_mov_b32 s49, 1
	v_mov_b32_e32 v18, 0
	s_branch .LBB0_59

.LBB0_120:
	s_abs_i32 s2, s58
	v_cvt_f32_u32_e32 v2, s2
	s_sub_i32 s4, 0, s2
	s_add_i32 s3, s58, s59
	v_rcp_iflag_f32_e32 v2, v2
	s_nop 0
	v_mul_f32_e32 v2, 0x4f7ffffe, v2
	v_cvt_u32_f32_e32 v2, v2
	s_nop 0
	v_readfirstlane_b32 s5, v2
	s_mul_i32 s4, s4, s5
	s_mul_hi_u32 s4, s5, s4
	s_add_i32 s5, s5, s4
	s_mul_hi_u32 s4, s5, 0x4a4
	s_mul_i32 s4, s4, s2
	s_sub_i32 s4, 0x4a4, s4
	s_sub_i32 s6, s4, s2
	s_cmp_ge_u32 s4, s2
	s_cselect_b32 s4, s6, s4
	s_sub_i32 s6, s4, s2
	s_cmp_ge_u32 s4, s2
	s_cselect_b32 s4, s6, s4
	s_sub_i32 s3, s3, s4
	s_ashr_i32 s4, s3, 31
	s_abs_i32 s3, s3
	s_mul_hi_u32 s5, s3, s5
	s_mul_i32 s5, s5, s2
	s_sub_i32 s3, s3, s5
	s_sub_i32 s5, s3, s2
	s_cmp_ge_u32 s3, s2
	s_cselect_b32 s3, s5, s3
	s_sub_i32 s5, s3, s2
	s_cmp_ge_u32 s3, s2
	s_cselect_b32 s2, s5, s3
	s_xor_b32 s2, s2, s4
	s_sub_i32 s18, s2, s4
	s_mov_b32 s97, s58
	s_cmpk_lg_i32 s58, 0x100
	s_cbranch_scc1 .Lpp_keep
	s_sub_i32 s18, s59, 0xa4
	s_cmp_lt_i32 s18, 0
	s_cselect_b32 s18, 0x108, s18
	s_movk_i32 s97, 0x5c
.Lpp_keep:
	s_cmpk_gt_i32 s18, 0x107
	s_cbranch_scc1 .LBB0_127
	s_add_u32 s19, s76, 0x1100000
	s_addc_u32 s20, s77, 0
	s_add_u32 s2, s76, 0xd35a000
	s_addc_u32 s3, s77, 0
	s_mov_b32 s21, 0x7fffe0
	v_mov_b32_e32 v131, 0
	s_add_i32 s22, 0, 0x18000
	s_mov_b64 s[4:5], 0x80
	s_add_i32 s23, 0, 0x1c000
	s_mov_b64 s[6:7], 0x100
	s_mov_b64 s[8:9], 0x180
	v_mov_b32_e32 v134, 1
	s_add_i32 s24, 0, 0x10000
	s_add_i32 s25, 0, 0x14000
	s_waitcnt vmcnt(0)
	s_branch .LBB0_123
.LBB0_122:
	s_lshl_b32 s13, s26, 6
	v_or_b32_e32 v130, s12, v132
	v_add_u32_e32 v132, s13, v130
	v_or_b32_e32 v130, s10, v133
	v_or_b32_e32 v136, s11, v130
	v_or_b32_e32 v138, 16, v132
	v_ashrrev_i32_e32 v133, 31, v132
	v_ashrrev_i32_e32 v139, 31, v138
	v_cvt_pk_bf16_f32 v122, v122, v123
	v_cvt_pk_bf16_f32 v123, v124, v125
	v_cvt_pk_bf16_f32 v124, v114, v115
	v_lshlrev_b64 v[114:115], 11, v[132:133]
	v_ashrrev_i32_e32 v137, 31, v136
	v_cvt_pk_bf16_f32 v125, v116, v117
	v_lshl_add_u64 v[116:117], s[2:3], 0, v[114:115]
	v_lshlrev_b64 v[114:115], 1, v[136:137]
	v_cvt_pk_bf16_f32 v102, v102, v103
	v_cvt_pk_bf16_f32 v103, v104, v105
	v_cvt_pk_bf16_f32 v104, v98, v99
	v_lshlrev_b64 v[98:99], 11, v[138:139]
	v_lshl_add_u64 v[136:137], v[116:117], 0, v[114:115]
	v_cvt_pk_bf16_f32 v116, v126, v127
	v_cvt_pk_bf16_f32 v117, v128, v129
	v_lshl_add_u64 v[98:99], s[2:3], 0, v[98:99]
	v_cvt_pk_bf16_f32 v118, v118, v119
	v_cvt_pk_bf16_f32 v119, v120, v121
	global_store_dwordx4 v[136:137], v[116:119], off offset:256
	v_cvt_pk_bf16_f32 v105, v100, v101
	v_cvt_pk_bf16_f32 v100, v106, v107
	v_cvt_pk_bf16_f32 v101, v108, v109
	v_cvt_pk_bf16_f32 v86, v86, v87
	v_cvt_pk_bf16_f32 v87, v88, v89
	s_nop 1
	v_lshl_add_u64 v[116:117], v[98:99], 0, v[114:115]
	v_cvt_pk_bf16_f32 v98, v110, v111
	v_cvt_pk_bf16_f32 v99, v112, v113
	global_store_dwordx4 v[116:117], v[98:101], off offset:256
	v_cvt_pk_bf16_f32 v88, v82, v83
	v_cvt_pk_bf16_f32 v70, v70, v71
	v_cvt_pk_bf16_f32 v71, v72, v73
	v_cvt_pk_bf16_f32 v72, v58, v59
	v_cvt_pk_bf16_f32 v89, v84, v85
	s_nop 1
	v_or_b32_e32 v100, 32, v132
	v_or_b32_e32 v98, 48, v132
	v_ashrrev_i32_e32 v101, 31, v100
	v_ashrrev_i32_e32 v99, 31, v98
	v_lshlrev_b64 v[82:83], 11, v[100:101]
	v_lshl_add_u64 v[82:83], s[2:3], 0, v[82:83]
	v_lshlrev_b64 v[58:59], 11, v[98:99]
	v_lshl_add_u64 v[100:101], v[82:83], 0, v[114:115]
	v_cvt_pk_bf16_f32 v82, v94, v95
	v_cvt_pk_bf16_f32 v83, v96, v97
	v_lshl_add_u64 v[58:59], s[2:3], 0, v[58:59]
	v_cvt_pk_bf16_f32 v84, v90, v91
	v_cvt_pk_bf16_f32 v85, v92, v93
	global_store_dwordx4 v[100:101], v[82:85], off offset:256
	v_cvt_pk_bf16_f32 v73, v60, v61
	v_cvt_pk_bf16_f32 v46, v46, v47
	v_cvt_pk_bf16_f32 v47, v48, v49
	v_cvt_pk_bf16_f32 v49, v40, v41
	v_cvt_pk_bf16_f32 v40, v34, v35
	s_nop 1
	v_lshl_add_u64 v[82:83], v[58:59], 0, v[114:115]
	global_store_dwordx4 v[82:83], v[70:73], off
	v_cvt_pk_bf16_f32 v41, v36, v37
	v_add_u32_e32 v34, 0xb0, v132
	v_add_u32_e32 v36, 0xa0, v132
	v_add_u32_e32 v70, 0x80, v132
	v_add_u32_e32 v72, 0x90, v132
	v_cvt_pk_bf16_f32 v60, v74, v75
	v_ashrrev_i32_e32 v73, 31, v72
	v_ashrrev_i32_e32 v71, 31, v70
	v_ashrrev_i32_e32 v35, 31, v34
	v_ashrrev_i32_e32 v37, 31, v36
	v_cvt_pk_bf16_f32 v58, v78, v79
	v_cvt_pk_bf16_f32 v59, v80, v81
	v_cvt_pk_bf16_f32 v61, v76, v77
	global_store_dwordx4 v[82:83], v[58:61], off offset:256
	v_cvt_pk_bf16_f32 v48, v38, v39
	v_lshlrev_b64 v[38:39], 11, v[72:73]
	v_cvt_pk_bf16_f32 v30, v30, v31
	v_cvt_pk_bf16_f32 v31, v32, v33
	v_cvt_pk_bf16_f32 v32, v22, v23
	s_nop 0
	v_cvt_pk_bf16_f32 v60, v54, v55
	v_lshlrev_b64 v[54:55], 11, v[70:71]
	v_lshlrev_b64 v[22:23], 11, v[36:37]
	v_cvt_pk_bf16_f32 v14, v14, v15
	v_cvt_pk_bf16_f32 v15, v16, v17
	v_cvt_pk_bf16_f32 v16, v6, v7
	v_lshlrev_b64 v[6:7], 11, v[34:35]
	v_lshl_add_u64 v[54:55], s[2:3], 0, v[54:55]
	v_lshl_add_u64 v[38:39], s[2:3], 0, v[38:39]
	v_lshl_add_u64 v[22:23], s[2:3], 0, v[22:23]
	v_lshl_add_u64 v[6:7], s[2:3], 0, v[6:7]
	s_add_i32 s18, s18, s97
	v_cvt_pk_bf16_f32 v58, v66, v67
	v_cvt_pk_bf16_f32 v61, v56, v57
	v_lshl_add_u64 v[66:67], v[54:55], 0, v[114:115]
	v_cvt_pk_bf16_f32 v56, v50, v51
	v_lshl_add_u64 v[50:51], v[38:39], 0, v[114:115]
	v_cvt_pk_bf16_f32 v33, v24, v25
	v_lshl_add_u64 v[36:37], v[22:23], 0, v[114:115]
	v_cvt_pk_bf16_f32 v24, v18, v19
	v_lshl_add_u64 v[18:19], v[6:7], 0, v[114:115]
	s_cmpk_gt_i32 s18, 0x107
	global_store_dwordx4 v[136:137], v[122:125], off
	global_store_dwordx4 v[116:117], v[102:105], off
	global_store_dwordx4 v[100:101], v[86:89], off
	v_cvt_pk_bf16_f32 v59, v68, v69
	global_store_dwordx4 v[66:67], v[58:61], off
	v_cvt_pk_bf16_f32 v54, v62, v63
	v_cvt_pk_bf16_f32 v55, v64, v65
	v_cvt_pk_bf16_f32 v57, v52, v53
	global_store_dwordx4 v[66:67], v[54:57], off offset:256
	global_store_dwordx4 v[50:51], v[46:49], off
	v_cvt_pk_bf16_f32 v38, v42, v43
	v_cvt_pk_bf16_f32 v39, v44, v45
	global_store_dwordx4 v[50:51], v[38:41], off offset:256
	global_store_dwordx4 v[36:37], v[30:33], off
	v_cvt_pk_bf16_f32 v22, v26, v27
	v_cvt_pk_bf16_f32 v23, v28, v29
	v_cvt_pk_bf16_f32 v25, v20, v21
	global_store_dwordx4 v[36:37], v[22:25], off offset:256
	v_cvt_pk_bf16_f32 v17, v8, v9
	global_store_dwordx4 v[18:19], v[14:17], off
	v_cvt_pk_bf16_f32 v6, v10, v11
	v_cvt_pk_bf16_f32 v7, v12, v13
	v_cvt_pk_bf16_f32 v8, v2, v3
	v_cvt_pk_bf16_f32 v9, v4, v5
	global_store_dwordx4 v[18:19], v[6:9], off offset:256
	s_waitcnt vmcnt(0)
	s_barrier
	s_cbranch_scc1 .LBB0_127
